# loader f32-expansion LDS writes made bank-conflict free (lane-pair exchange); cg grid.sync replaced by XCD barrier copy
# speedup vs baseline: 1.0178x; 1.0178x over previous
.LBB0_72:
	v_mov_b32_e32 v145, 0
	v_mov_b32_e32 v227, 0x1000
	v_mov_b32_e32 v228, 0x2000
	v_mov_b32_e32 v230, 1
	s_load_dword s0, s[38:39], 0xd8
	s_mul_i32 s73, s41, s40
	s_waitcnt lgkmcnt(0)
	s_mul_i32 s73, s73, s0
	s_mov_b32 s6, s38
	s_mov_b32 s7, s39
	s_getreg_b32 s8, hwreg(HW_REG_XCC_ID, 0, 4)
	s_waitcnt vmcnt(0)
	v_mov_b32_e32 v0, v226
	s_barrier
	s_nop 0
	v_cmp_eq_u32_e32 vcc, 0, v0
	s_and_saveexec_b64 s[4:5], vcc
	s_xor_b64 s[4:5], exec, s[4:5]
	s_cbranch_execz .Lpre_147
	s_mov_b32 s0, 0x24000
	s_load_dwordx2 s[6:7], s[6:7], 0xc0
	s_waitcnt vmcnt(0) expcnt(0) lgkmcnt(0)
	v_mov_b32_e32 v0, s0
	ds_read_b32 v2, v0
	s_mov_b32 s0, 0x24004
	s_and_b32 s72, s8, 15
	s_waitcnt lgkmcnt(0)
	v_cmp_ne_u32_e32 vcc, 0, v2
	v_mov_b32_e32 v0, s0
	ds_read_b32 v0, v0
	s_cbranch_vccnz .Lpre_110
	s_add_u32 s8, s6, 0x1ebfd300
	s_addc_u32 s9, s7, 0
	s_add_u32 s10, s6, 0x1ebfd500
	s_addc_u32 s11, s7, 0
	s_add_u32 s12, s6, 0x1ebfd600
	s_addc_u32 s13, s7, 0
	s_add_u32 s14, s6, 0x1ebfd700
	s_addc_u32 s15, s7, 0
	s_add_u32 s16, s6, 0x1ebfd800
	s_addc_u32 s17, s7, 0
	s_add_u32 s18, s6, 0x1ebfd900
	s_addc_u32 s19, s7, 0
	s_add_u32 s20, s6, 0x1ebfda00
	s_addc_u32 s21, s7, 0
	s_add_u32 s22, s6, 0x1ebfdb00
	s_addc_u32 s23, s7, 0
	s_add_u32 s24, s6, 0x1ebfdc00
	s_addc_u32 s25, s7, 0
	s_add_u32 s26, s6, 0x1ebfdd00
	s_addc_u32 s27, s7, 0
	s_add_u32 s28, s6, 0x1ebfde00
	s_addc_u32 s29, s7, 0
	s_add_u32 s30, s6, 0x1ebfdf00
	s_addc_u32 s31, s7, 0
	s_add_u32 s34, s6, 0x1ebfe000
	s_addc_u32 s35, s7, 0
	s_add_u32 s36, s6, 0x1ebfe100
	s_addc_u32 s37, s7, 0
	s_add_u32 s44, s6, 0x1ebfe200
	s_addc_u32 s45, s7, 0
	s_add_u32 s58, s6, 0x1ebfe300
	s_addc_u32 s59, s7, 0
	s_add_u32 s92, s6, 0x1ebfe400
	s_addc_u32 s93, s7, 0
	s_mov_b32 s33, 1
	s_branch .Lpre_98

.Lpre_109:
	s_cmp_eq_u32 s72, 0
	s_cselect_b64 vcc, -1, 0
	s_cmp_eq_u32 s72, 1
	v_cndmask_b32_e32 v16, 0, v15, vcc
	s_cselect_b64 vcc, -1, 0
	s_cmp_eq_u32 s72, 2
	v_cndmask_b32_e32 v16, v16, v0, vcc
	s_cselect_b64 vcc, -1, 0
	s_cmp_eq_u32 s72, 3
	v_cndmask_b32_e32 v16, v16, v1, vcc
	s_cselect_b64 vcc, -1, 0
	s_cmp_eq_u32 s72, 4
	v_cndmask_b32_e32 v16, v16, v2, vcc
	s_cselect_b64 vcc, -1, 0
	s_cmp_eq_u32 s72, 5
	v_cndmask_b32_e32 v16, v16, v3, vcc
	s_cselect_b64 vcc, -1, 0
	s_cmp_eq_u32 s72, 6
	v_cndmask_b32_e32 v16, v16, v4, vcc
	s_cselect_b64 vcc, -1, 0
	s_cmp_eq_u32 s72, 7
	v_cndmask_b32_e32 v16, v16, v5, vcc
	s_cselect_b64 vcc, -1, 0
	s_cmp_eq_u32 s72, 8
	v_cndmask_b32_e32 v16, v16, v6, vcc
	s_cselect_b64 vcc, -1, 0
	s_cmp_eq_u32 s72, 9
	v_cndmask_b32_e32 v16, v16, v7, vcc
	s_cselect_b64 vcc, -1, 0
	s_cmp_eq_u32 s72, 10
	v_cndmask_b32_e32 v16, v16, v8, vcc
	s_cselect_b64 vcc, -1, 0
	s_cmp_eq_u32 s72, 11
	v_cndmask_b32_e32 v16, v16, v9, vcc
	s_cselect_b64 vcc, -1, 0
	s_cmp_eq_u32 s72, 12
	v_cndmask_b32_e32 v16, v16, v10, vcc
	s_cselect_b64 vcc, -1, 0
	s_cmp_eq_u32 s72, 13
	v_cndmask_b32_e32 v16, v16, v11, vcc
	s_cselect_b64 vcc, -1, 0
	s_cmp_eq_u32 s72, 14
	v_cndmask_b32_e32 v16, v16, v12, vcc
	s_cselect_b64 vcc, -1, 0
	s_cmp_eq_u32 s72, 15
	v_cndmask_b32_e32 v16, v16, v13, vcc
	s_cselect_b64 vcc, -1, 0
	v_cndmask_b32_e32 v16, v16, v14, vcc
	v_cmp_ne_u32_e32 vcc, 0, v15
	s_mov_b32 s0, 0x24000
	s_nop 0
	v_cndmask_b32_e64 v15, 0, 1, vcc
	v_cmp_ne_u32_e32 vcc, 0, v0
	s_nop 1
	v_addc_co_u32_e32 v0, vcc, 0, v15, vcc
	v_cmp_ne_u32_e32 vcc, 0, v1
	s_nop 1
	v_cndmask_b32_e64 v1, 0, 1, vcc
	v_cmp_ne_u32_e32 vcc, 0, v2
	v_max_u32_e32 v2, 1, v16
	s_nop 0
	v_addc_co_u32_e32 v0, vcc, v0, v1, vcc
	v_cmp_ne_u32_e32 vcc, 0, v3
	s_nop 1
	v_cndmask_b32_e64 v1, 0, 1, vcc
	v_cmp_ne_u32_e32 vcc, 0, v4
	s_nop 1
	v_addc_co_u32_e32 v0, vcc, v0, v1, vcc
	v_cmp_ne_u32_e32 vcc, 0, v5
	s_nop 1
	v_cndmask_b32_e64 v1, 0, 1, vcc
	v_cmp_ne_u32_e32 vcc, 0, v6
	s_nop 1
	v_addc_co_u32_e32 v0, vcc, v0, v1, vcc
	v_cmp_ne_u32_e32 vcc, 0, v7
	s_nop 1
	v_cndmask_b32_e64 v1, 0, 1, vcc
	v_cmp_ne_u32_e32 vcc, 0, v8
	s_nop 1
	v_addc_co_u32_e32 v0, vcc, v0, v1, vcc
	v_cmp_ne_u32_e32 vcc, 0, v9
	s_nop 1
	v_cndmask_b32_e64 v1, 0, 1, vcc
	v_cmp_ne_u32_e32 vcc, 0, v10
	s_nop 1
	v_addc_co_u32_e32 v0, vcc, v0, v1, vcc
	v_cmp_ne_u32_e32 vcc, 0, v11
	s_nop 1
	v_cndmask_b32_e64 v1, 0, 1, vcc
	v_cmp_ne_u32_e32 vcc, 0, v12
	s_nop 1
	v_addc_co_u32_e32 v0, vcc, v0, v1, vcc
	v_cmp_ne_u32_e32 vcc, 0, v13
	s_nop 1
	v_cndmask_b32_e64 v1, 0, 1, vcc
	v_cmp_ne_u32_e32 vcc, 0, v14
	s_nop 1
	v_addc_co_u32_e32 v0, vcc, v0, v1, vcc
	v_mov_b32_e32 v1, s0
	s_mov_b32 s0, 0x24004
	v_max_u32_e32 v0, 1, v0
	ds_write_b32 v1, v2
	v_mov_b32_e32 v1, s0
	ds_write_b32 v1, v0

.Lpre_147:
	s_or_b64 exec, exec, s[4:5]
	s_waitcnt lgkmcnt(0)
	s_barrier

.LBB0_791:
	s_andn2_saveexec_b64 s[36:37], s[36:37]
	s_cbranch_execz .LBB0_786
	s_cmp_eq_u32 s34, 0x379000
	s_cbranch_scc1 .LBB0_823
	s_andn2_b32 s0, 1, s54
	s_mul_i32 s0, s0, 0xc000
	s_add_i32 s4, s0, 0
	v_add_u32_e32 v28, s4, v103
	s_and_saveexec_b64 s[0:1], s[10:11]
	s_xor_b64 s[44:45], exec, s[0:1]
	s_cbranch_execz .LBB0_795
	v_lshl_add_u32 v28, v104, 2, v28
	v_add3_u32 v36, v28, v127, s53
	s_waitcnt vmcnt(6)
	s_mov_b32 vcc_lo, 0xaaaaaaaa
	s_mov_b32 vcc_hi, 0xaaaaaaaa
	v_cndmask_b32_e32 v37, v2, v0, vcc
	v_cndmask_b32_e32 v38, v3, v1, vcc
	v_add_u32_e32 v40, -16, v36
	v_cndmask_b32_e32 v36, v36, v40, vcc
	v_mov_b32_dpp v41, v37 quad_perm:[1,0,3,2] row_mask:0xf bank_mask:0xf bound_ctrl:1
	v_mov_b32_dpp v42, v38 quad_perm:[1,0,3,2] row_mask:0xf bank_mask:0xf bound_ctrl:1
	v_cndmask_b32_e32 v37, v0, v41, vcc
	v_cndmask_b32_e32 v38, v1, v42, vcc
	v_cndmask_b32_e32 v41, v41, v2, vcc
	v_cndmask_b32_e32 v42, v42, v3, vcc
	v_lshlrev_b32_e32 v28, 16, v37
	v_and_b32_e32 v29, 0xffff0000, v37
	v_lshlrev_b32_e32 v30, 16, v38
	v_and_b32_e32 v31, 0xffff0000, v38
	ds_write_b128 v36, v[28:31]
	v_lshlrev_b32_e32 v28, 16, v41
	v_and_b32_e32 v29, 0xffff0000, v41
	v_lshlrev_b32_e32 v30, 16, v42
	v_and_b32_e32 v31, 0xffff0000, v42
	ds_write_b128 v36, v[28:31] offset:32

.LBB0_797:
	s_or_b64 exec, exec, s[44:45]
	v_add_u32_e32 v28, s4, v106
	s_and_saveexec_b64 s[0:1], s[12:13]
	s_xor_b64 s[44:45], exec, s[0:1]
	s_cbranch_execz .LBB0_799
	v_lshl_add_u32 v28, v107, 2, v28
	v_add3_u32 v36, v28, v128, s53
	s_waitcnt vmcnt(5)
	s_mov_b32 vcc_lo, 0xaaaaaaaa
	s_mov_b32 vcc_hi, 0xaaaaaaaa
	v_cndmask_b32_e32 v37, v6, v4, vcc
	v_cndmask_b32_e32 v38, v7, v5, vcc
	v_add_u32_e32 v40, -16, v36
	v_cndmask_b32_e32 v36, v36, v40, vcc
	v_mov_b32_dpp v41, v37 quad_perm:[1,0,3,2] row_mask:0xf bank_mask:0xf bound_ctrl:1
	v_mov_b32_dpp v42, v38 quad_perm:[1,0,3,2] row_mask:0xf bank_mask:0xf bound_ctrl:1
	v_cndmask_b32_e32 v37, v4, v41, vcc
	v_cndmask_b32_e32 v38, v5, v42, vcc
	v_cndmask_b32_e32 v41, v41, v6, vcc
	v_cndmask_b32_e32 v42, v42, v7, vcc
	v_lshlrev_b32_e32 v28, 16, v37
	v_and_b32_e32 v29, 0xffff0000, v37
	v_lshlrev_b32_e32 v30, 16, v38
	v_and_b32_e32 v31, 0xffff0000, v38
	ds_write_b128 v36, v[28:31]
	v_lshlrev_b32_e32 v28, 16, v41
	v_and_b32_e32 v29, 0xffff0000, v41
	v_lshlrev_b32_e32 v30, 16, v42
	v_and_b32_e32 v31, 0xffff0000, v42
	ds_write_b128 v36, v[28:31] offset:32

.LBB0_801:
	s_or_b64 exec, exec, s[44:45]
	v_add_u32_e32 v28, s4, v109
	s_and_saveexec_b64 s[0:1], s[14:15]
	s_xor_b64 s[44:45], exec, s[0:1]
	s_cbranch_execz .LBB0_803
	v_lshl_add_u32 v28, v110, 2, v28
	v_add3_u32 v36, v28, v129, s53
	s_waitcnt vmcnt(4)
	s_mov_b32 vcc_lo, 0xaaaaaaaa
	s_mov_b32 vcc_hi, 0xaaaaaaaa
	v_cndmask_b32_e32 v37, v10, v8, vcc
	v_cndmask_b32_e32 v38, v11, v9, vcc
	v_add_u32_e32 v40, -16, v36
	v_cndmask_b32_e32 v36, v36, v40, vcc
	v_mov_b32_dpp v41, v37 quad_perm:[1,0,3,2] row_mask:0xf bank_mask:0xf bound_ctrl:1
	v_mov_b32_dpp v42, v38 quad_perm:[1,0,3,2] row_mask:0xf bank_mask:0xf bound_ctrl:1
	v_cndmask_b32_e32 v37, v8, v41, vcc
	v_cndmask_b32_e32 v38, v9, v42, vcc
	v_cndmask_b32_e32 v41, v41, v10, vcc
	v_cndmask_b32_e32 v42, v42, v11, vcc
	v_lshlrev_b32_e32 v28, 16, v37
	v_and_b32_e32 v29, 0xffff0000, v37
	v_lshlrev_b32_e32 v30, 16, v38
	v_and_b32_e32 v31, 0xffff0000, v38
	ds_write_b128 v36, v[28:31]
	v_lshlrev_b32_e32 v28, 16, v41
	v_and_b32_e32 v29, 0xffff0000, v41
	v_lshlrev_b32_e32 v30, 16, v42
	v_and_b32_e32 v31, 0xffff0000, v42
	ds_write_b128 v36, v[28:31] offset:32

.LBB0_805:
	s_or_b64 exec, exec, s[44:45]
	v_add_u32_e32 v28, s4, v112
	s_and_saveexec_b64 s[0:1], s[16:17]
	s_xor_b64 s[44:45], exec, s[0:1]
	s_cbranch_execz .LBB0_807
	v_lshl_add_u32 v28, v113, 2, v28
	v_add3_u32 v36, v28, v130, s53
	s_waitcnt vmcnt(3)
	s_mov_b32 vcc_lo, 0xaaaaaaaa
	s_mov_b32 vcc_hi, 0xaaaaaaaa
	v_cndmask_b32_e32 v37, v14, v12, vcc
	v_cndmask_b32_e32 v38, v15, v13, vcc
	v_add_u32_e32 v40, -16, v36
	v_cndmask_b32_e32 v36, v36, v40, vcc
	v_mov_b32_dpp v41, v37 quad_perm:[1,0,3,2] row_mask:0xf bank_mask:0xf bound_ctrl:1
	v_mov_b32_dpp v42, v38 quad_perm:[1,0,3,2] row_mask:0xf bank_mask:0xf bound_ctrl:1
	v_cndmask_b32_e32 v37, v12, v41, vcc
	v_cndmask_b32_e32 v38, v13, v42, vcc
	v_cndmask_b32_e32 v41, v41, v14, vcc
	v_cndmask_b32_e32 v42, v42, v15, vcc
	v_lshlrev_b32_e32 v28, 16, v37
	v_and_b32_e32 v29, 0xffff0000, v37
	v_lshlrev_b32_e32 v30, 16, v38
	v_and_b32_e32 v31, 0xffff0000, v38
	ds_write_b128 v36, v[28:31]
	v_lshlrev_b32_e32 v28, 16, v41
	v_and_b32_e32 v29, 0xffff0000, v41
	v_lshlrev_b32_e32 v30, 16, v42
	v_and_b32_e32 v31, 0xffff0000, v42
	ds_write_b128 v36, v[28:31] offset:32

.LBB0_809:
	s_or_b64 exec, exec, s[44:45]
	v_add_u32_e32 v28, s4, v115
	s_and_saveexec_b64 s[0:1], s[18:19]
	s_xor_b64 s[44:45], exec, s[0:1]
	s_cbranch_execz .LBB0_811
	v_lshl_add_u32 v28, v116, 2, v28
	v_add3_u32 v36, v28, v131, s53
	s_waitcnt vmcnt(2)
	s_mov_b32 vcc_lo, 0xaaaaaaaa
	s_mov_b32 vcc_hi, 0xaaaaaaaa
	v_cndmask_b32_e32 v37, v18, v16, vcc
	v_cndmask_b32_e32 v38, v19, v17, vcc
	v_add_u32_e32 v40, -16, v36
	v_cndmask_b32_e32 v36, v36, v40, vcc
	v_mov_b32_dpp v41, v37 quad_perm:[1,0,3,2] row_mask:0xf bank_mask:0xf bound_ctrl:1
	v_mov_b32_dpp v42, v38 quad_perm:[1,0,3,2] row_mask:0xf bank_mask:0xf bound_ctrl:1
	v_cndmask_b32_e32 v37, v16, v41, vcc
	v_cndmask_b32_e32 v38, v17, v42, vcc
	v_cndmask_b32_e32 v41, v41, v18, vcc
	v_cndmask_b32_e32 v42, v42, v19, vcc
	v_lshlrev_b32_e32 v28, 16, v37
	v_and_b32_e32 v29, 0xffff0000, v37
	v_lshlrev_b32_e32 v30, 16, v38
	v_and_b32_e32 v31, 0xffff0000, v38
	ds_write_b128 v36, v[28:31]
	v_lshlrev_b32_e32 v28, 16, v41
	v_and_b32_e32 v29, 0xffff0000, v41
	v_lshlrev_b32_e32 v30, 16, v42
	v_and_b32_e32 v31, 0xffff0000, v42
	ds_write_b128 v36, v[28:31] offset:32

.LBB0_813:
	s_or_b64 exec, exec, s[44:45]
	v_add_u32_e32 v28, s4, v118
	s_and_saveexec_b64 s[0:1], s[20:21]
	s_xor_b64 s[44:45], exec, s[0:1]
	s_cbranch_execz .LBB0_815
	v_lshl_add_u32 v28, v119, 2, v28
	v_add3_u32 v36, v28, v132, s53
	s_waitcnt vmcnt(1)
	s_mov_b32 vcc_lo, 0xaaaaaaaa
	s_mov_b32 vcc_hi, 0xaaaaaaaa
	v_cndmask_b32_e32 v37, v22, v20, vcc
	v_cndmask_b32_e32 v38, v23, v21, vcc
	v_add_u32_e32 v40, -16, v36
	v_cndmask_b32_e32 v36, v36, v40, vcc
	v_mov_b32_dpp v41, v37 quad_perm:[1,0,3,2] row_mask:0xf bank_mask:0xf bound_ctrl:1
	v_mov_b32_dpp v42, v38 quad_perm:[1,0,3,2] row_mask:0xf bank_mask:0xf bound_ctrl:1
	v_cndmask_b32_e32 v37, v20, v41, vcc
	v_cndmask_b32_e32 v38, v21, v42, vcc
	v_cndmask_b32_e32 v41, v41, v22, vcc
	v_cndmask_b32_e32 v42, v42, v23, vcc
	v_lshlrev_b32_e32 v28, 16, v37
	v_and_b32_e32 v29, 0xffff0000, v37
	v_lshlrev_b32_e32 v30, 16, v38
	v_and_b32_e32 v31, 0xffff0000, v38
	ds_write_b128 v36, v[28:31]
	v_lshlrev_b32_e32 v28, 16, v41
	v_and_b32_e32 v29, 0xffff0000, v41
	v_lshlrev_b32_e32 v30, 16, v42
	v_and_b32_e32 v31, 0xffff0000, v42
	ds_write_b128 v36, v[28:31] offset:32

.LBB0_817:
	s_or_b64 exec, exec, s[44:45]
	v_add_u32_e32 v28, s4, v122
	s_and_saveexec_b64 s[0:1], s[22:23]
	s_xor_b64 s[44:45], exec, s[0:1]
	s_cbranch_execz .LBB0_819
	v_lshl_add_u32 v28, v123, 2, v28
	v_add3_u32 v36, v28, v133, s53
	s_waitcnt vmcnt(0)
	s_mov_b32 vcc_lo, 0xaaaaaaaa
	s_mov_b32 vcc_hi, 0xaaaaaaaa
	v_cndmask_b32_e32 v37, v26, v24, vcc
	v_cndmask_b32_e32 v38, v27, v25, vcc
	v_add_u32_e32 v40, -16, v36
	v_cndmask_b32_e32 v36, v36, v40, vcc
	v_mov_b32_dpp v41, v37 quad_perm:[1,0,3,2] row_mask:0xf bank_mask:0xf bound_ctrl:1
	v_mov_b32_dpp v42, v38 quad_perm:[1,0,3,2] row_mask:0xf bank_mask:0xf bound_ctrl:1
	v_cndmask_b32_e32 v37, v24, v41, vcc
	v_cndmask_b32_e32 v38, v25, v42, vcc
	v_cndmask_b32_e32 v41, v41, v26, vcc
	v_cndmask_b32_e32 v42, v42, v27, vcc
	v_lshlrev_b32_e32 v28, 16, v37
	v_and_b32_e32 v29, 0xffff0000, v37
	v_lshlrev_b32_e32 v30, 16, v38
	v_and_b32_e32 v31, 0xffff0000, v38
	ds_write_b128 v36, v[28:31]
	v_lshlrev_b32_e32 v28, 16, v41
	v_and_b32_e32 v29, 0xffff0000, v41
	v_lshlrev_b32_e32 v30, 16, v42
	v_and_b32_e32 v31, 0xffff0000, v42
	ds_write_b128 v36, v[28:31] offset:32
